# V^T GEMM epilogue: 8-byte store pairs merged into 16-byte stores via v_permlane16_swap (same bytes, same values)
# baseline (speedup 1.0000x reference)
; #define PG8_STAGE(bufoff, gbase, voff) do { _Pragma("unroll") for (int _i = 0; _i < 2; ++_i) \
;         __builtin_amdgcn_global_load_lds((const unsigned*)((const char*)(gbase) + (voff)[_i]), (PG8_LAS unsigned*)(lds + (bufoff) + ldsw + _i * 8192), 16, 0, 0); } while (0)
; #define PG8_WAIT_V(n) asm volatile("s_waitcnt vmcnt(" #n ")" ::: "memory")
; #define PG8_BAR __builtin_amdgcn_s_barrier()
;     __device__ __forceinline__ void operator()(const f32x4 (&acc)[2][2][4][2], const Unit& u, int wr, int wc, int fr, int fq) const {
;     ...
;                 for (int bj = 0; bj < 2; ++bj) { const int col = col0 + bj * HALF, b = col >> 12, tl = col & 4095, kt = tl >> 5, k0 = tl & 31, s = k0 >> 4, half = (k0 >> 3) & 1, bh = b * 16 + h;
;                     const f32x4 v0 = acc[ai][bj][m][0] * cs[bj][0], v1 = acc[ai][bj][m][1] * cs[bj][1];
;                     bf16_t* p = VF + (((size_t)((((bh * 128 + kt) * 2 + dt) * 2 + s) * 64 + r)) << 3) + 4 * half;
; template <class Epi, class Sched, bool ALIGN_EPI = false, bool SP2 = false>
; __device__ __forceinline__ void gemm_phase(PG8_LAS unsigned char* lds, const Gemm g, const Sched& S, const Epi& E) {
;     ...
;         PG8_STAGE(PG8_SB(1, 0), cB + kstep, voffB); PG8_STAGE(PG8_SA(1, 0), cA + kstep, voffA); PG8_STAGE(PG8_SB(1, 1), cB + hstep + kstep, voffB);
;         PG8_WAIT_V(6); PG8_BAR;
.LBB0_568:
	s_lshl_b32 s39, s4, 6
	s_lshl_b32 s12, s4, 13
	s_mov_b64 s[4:5], 0x80
	s_lshl_b32 s3, s3, 5
	s_add_i32 m0, s19, 0x18000
	v_lshl_add_u64 v[6:7], v[6:7], 0, s[4:5]
	s_and_b32 s42, s3, 0x60
	s_waitcnt vmcnt(2)
	s_barrier
	global_load_lds_dwordx4 v[6:7], off
	v_lshl_add_u64 v[4:5], v[4:5], 0, s[4:5]
	s_add_i32 m0, s19, 0x1a000
	s_add_i32 s43, s19, 0x8000
	s_add_i32 s44, s19, 0xa000
	global_load_lds_dwordx4 v[4:5], off
	v_lshl_add_u64 v[2:3], v[2:3], 0, s[4:5]
	s_mov_b32 m0, s43
	s_add_u32 s10, s22, 0x40080
	global_load_lds_dwordx4 v[2:3], off
	v_lshl_add_u64 v[0:1], v[0:1], 0, s[4:5]
	s_mov_b32 m0, s44
	s_addc_u32 s11, s23, 0
	global_load_lds_dwordx4 v[0:1], off
	s_add_i32 m0, s19, 0x1c000
	v_lshl_add_u64 v[0:1], s[10:11], 0, v[130:131]
	global_load_lds_dwordx4 v[0:1], off
	v_lshl_add_u64 v[0:1], s[10:11], 0, v[134:135]
	s_add_i32 m0, s19, 0x1e000
	s_sext_i32_i16 s49, s2
	global_load_lds_dwordx4 v[0:1], off
	v_lshlrev_b32_e32 v1, 2, v162
	v_lshl_or_b32 v0, v162, 6, v155
	v_and_b32_e32 v1, 32, v1
	v_bitop3_b32 v2, v0, s12, v1 bitop3:0xde
	v_lshlrev_b32_e32 v0, 9, v8
	v_and_b32_e32 v0, 0x200, v0
	v_mov_b32_e32 v1, v131
	v_lshl_add_u64 v[0:1], s[54:55], 0, v[0:1]
	s_mov_b64 s[2:3], 0x9c00000
	v_lshl_add_u64 v[136:137], v[0:1], 0, s[2:3]
	v_lshlrev_b32_e32 v0, 8, v184
	v_and_b32_e32 v0, 0x38000, v0
	v_lshlrev_b32_e32 v1, 11, v152
	v_or3_b32 v0, v150, v0, v1
	v_add_u32_e32 v138, v0, v151
	v_lshlrev_b32_e32 v0, 4, v153
	s_waitcnt vmcnt(6)
	v_and_b32_e32 v0, 0x78000, v0
	v_lshl_or_b32 v164, s42, 7, v156
	v_or3_b32 v0, v150, v0, v1
	s_add_i32 s47, 0, 0x10000
	s_add_i32 s48, 0, 0x14000
	v_lshlrev_b32_e32 v163, 3, v154
	v_lshrrev_b32_e32 v165, 1, v154
	v_or_b32_e32 v166, 16, v162
	s_ashr_i32 s45, s64, 31
	s_mov_b32 s46, s64
	v_mov_b32_e32 v139, v131
	v_add_u32_e32 v140, v0, v151
	v_mov_b32_e32 v141, v131
	v_mov_b64_e32 v[142:143], 0x100
	v_mov_b64_e32 v[144:145], 0xff
	v_add_u32_e32 v167, s47, v164
	v_add_u32_e32 v168, s48, v164
	v_add_u32_e32 v169, 0, v2
	v_mov_b32_e32 v170, 0x358637bd
	s_barrier

; #define PG8_STAGE(bufoff, gbase, voff) do { _Pragma("unroll") for (int _i = 0; _i < 2; ++_i) \
;         __builtin_amdgcn_global_load_lds((const unsigned*)((const char*)(gbase) + (voff)[_i]), (PG8_LAS unsigned*)(lds + (bufoff) + ldsw + _i * 8192), 16, 0, 0); } while (0)
; #define PG8_LDA(dst, b, h) do { _Pragma("unroll") for (int m = 0; m < 4; ++m) _Pragma("unroll") for (int k = 0; k < 2; ++k) dst[m][k] = *(const PG8_LAS bf16x8*)(lds + PG8_SA(b, h) + aoff + m * 2048 + k * 1024); } while (0)
; #define PG8_LDB(dst, b, h) do { _Pragma("unroll") for (int n = 0; n < 2; ++n) _Pragma("unroll") for (int k = 0; k < 2; ++k) dst[n][k] = *(const PG8_LAS bf16x8*)(lds + PG8_SB(b, h) + boff + n * 2048 + k * 1024); } while (0)
; #define PG8_MMA(ai, bj, At, Bt) do { __builtin_amdgcn_s_setprio(1); _Pragma("unroll") for (int m = 0; m < 4; ++m) _Pragma("unroll") for (int n = 0; n < 2; ++n) _Pragma("unroll") for (int k = 0; k < 2; ++k) \
;         acc[ai][bj][m][n] = __builtin_amdgcn_mfma_f32_16x16x32_bf16(Bt[n][k], At[m][k], acc[ai][bj][m][n], 0, 0, 0); __builtin_amdgcn_s_setprio(0); } while (0)
; #define PG8_WAIT_V(n) asm volatile("s_waitcnt vmcnt(" #n ")" ::: "memory")
; #define PG8_WAIT_L(n) asm volatile("s_waitcnt lgkmcnt(" #n ")" ::: "memory")
; #define PG8_BAR __builtin_amdgcn_s_barrier()
; #define PG8_SCHED __builtin_amdgcn_sched_barrier(0)
; template <class Epi, class Sched, bool ALIGN_EPI = false, bool SP2 = false>
; __device__ __forceinline__ void gemm_phase(PG8_LAS unsigned char* lds, const Gemm g, const Sched& S, const Epi& E) {
;     ...
;             PG8_LDB(B0, 0, 0); PG8_LDB(B1, 0, 1); PG8_SCHED; PG8_LDA(At, 0, 0); PG8_STAGE(PG8_SA(1, 1), a1 + hstep, voffA);
;             PG8_WAIT_V(8); PG8_WAIT_L(0); PG8_BAR; PG8_MMA(0, 0, At, B0); PG8_MMA(0, 1, At, B1); PG8_BAR; PG8_SCHED;
;             PG8_LDA(At, 0, 1); PG8_STAGE(PG8_SB(0, 0), b2, voffB); PG8_STAGE(PG8_SB(0, 1), b2 + hstep, voffB); PG8_STAGE(PG8_SA(0, 0), a2, voffA);
;             PG8_WAIT_V(8); PG8_WAIT_L(0); PG8_BAR; PG8_MMA(1, 0, At, B0); PG8_MMA(1, 1, At, B1); PG8_BAR; PG8_SCHED;
.LBB0_576:
	ds_read_b128 v[146:149], v167
	ds_read_b128 v[150:153], v167 offset:1024
	ds_read_b128 v[154:157], v167 offset:2048
	ds_read_b128 v[158:161], v167 offset:3072
	ds_read_b128 v[172:175], v168
	ds_read_b128 v[176:179], v168 offset:1024
	ds_read_b128 v[180:183], v168 offset:2048
	ds_read_b128 v[188:191], v168 offset:3072
	s_add_u32 s22, s20, 0xfffc0080
	s_addc_u32 s23, s21, -1
	s_cmp_eq_u32 s70, 12
	s_cselect_b32 s25, s13, s23
	s_cselect_b32 s24, s50, s22
	s_cselect_b32 s23, s11, s69
	s_cselect_b32 s22, s51, s58
	v_lshl_add_u64 v[224:225], s[20:21], 0, v[138:139]
	s_add_i32 m0, s19, 0xc000
	ds_read_b128 v[192:195], v169
	ds_read_b128 v[196:199], v169 offset:1024
	ds_read_b128 v[200:203], v169 offset:2048
	ds_read_b128 v[204:207], v169 offset:3072
	ds_read_b128 v[208:211], v169 offset:4096
	ds_read_b128 v[212:215], v169 offset:5120
	ds_read_b128 v[216:219], v169 offset:6144
	ds_read_b128 v[220:223], v169 offset:7168
	global_load_lds_dwordx4 v[224:225], off
	v_lshl_add_u64 v[224:225], s[20:21], 0, v[140:141]
	s_add_i32 m0, s19, 0xe000
	s_nop 0
	global_load_lds_dwordx4 v[224:225], off
	s_waitcnt vmcnt(8)
	s_waitcnt lgkmcnt(0)
	s_barrier
	s_setprio 1
	s_waitcnt lgkmcnt(0)
	v_mfma_f32_16x16x32_bf16 v[124:127], v[146:149], v[192:195], v[124:127]
	v_mfma_f32_16x16x32_bf16 v[120:123], v[154:157], v[192:195], v[120:123]
	v_mfma_f32_16x16x32_bf16 v[116:119], v[146:149], v[200:203], v[116:119]
	v_mfma_f32_16x16x32_bf16 v[112:115], v[154:157], v[200:203], v[112:115]
	v_mfma_f32_16x16x32_bf16 v[92:95], v[146:149], v[208:211], v[92:95]
	v_mfma_f32_16x16x32_bf16 v[88:91], v[154:157], v[208:211], v[88:91]
	v_mfma_f32_16x16x32_bf16 v[76:79], v[146:149], v[216:219], v[76:79]
	v_mfma_f32_16x16x32_bf16 v[72:75], v[154:157], v[216:219], v[72:75]
	v_mfma_f32_16x16x32_bf16 v[124:127], v[150:153], v[196:199], v[124:127]
	v_mfma_f32_16x16x32_bf16 v[120:123], v[158:161], v[196:199], v[120:123]
	v_mfma_f32_16x16x32_bf16 v[116:119], v[150:153], v[204:207], v[116:119]
	v_mfma_f32_16x16x32_bf16 v[112:115], v[158:161], v[204:207], v[112:115]
	v_mfma_f32_16x16x32_bf16 v[92:95], v[150:153], v[212:215], v[92:95]
	v_mfma_f32_16x16x32_bf16 v[88:91], v[158:161], v[212:215], v[88:91]
	v_mfma_f32_16x16x32_bf16 v[76:79], v[150:153], v[220:223], v[76:79]
	v_mfma_f32_16x16x32_bf16 v[72:75], v[158:161], v[220:223], v[72:75]
	s_setprio 0
	s_setprio 1
	v_mfma_f32_16x16x32_bf16 v[108:111], v[172:175], v[192:195], v[108:111]
	v_mfma_f32_16x16x32_bf16 v[104:107], v[180:183], v[192:195], v[104:107]
	v_mfma_f32_16x16x32_bf16 v[100:103], v[172:175], v[200:203], v[100:103]
	v_mfma_f32_16x16x32_bf16 v[96:99], v[180:183], v[200:203], v[96:99]
	v_mfma_f32_16x16x32_bf16 v[84:87], v[172:175], v[208:211], v[84:87]
	v_mfma_f32_16x16x32_bf16 v[80:83], v[180:183], v[208:211], v[80:83]
	v_mfma_f32_16x16x32_bf16 v[68:71], v[172:175], v[216:219], v[68:71]
	v_mfma_f32_16x16x32_bf16 v[64:67], v[180:183], v[216:219], v[64:67]
	v_mfma_f32_16x16x32_bf16 v[108:111], v[176:179], v[196:199], v[108:111]
	v_mfma_f32_16x16x32_bf16 v[104:107], v[188:191], v[196:199], v[104:107]
	v_mfma_f32_16x16x32_bf16 v[100:103], v[176:179], v[204:207], v[100:103]
	v_mfma_f32_16x16x32_bf16 v[96:99], v[188:191], v[204:207], v[96:99]
	v_mfma_f32_16x16x32_bf16 v[84:87], v[176:179], v[212:215], v[84:87]
	v_mfma_f32_16x16x32_bf16 v[80:83], v[188:191], v[212:215], v[80:83]
	v_mfma_f32_16x16x32_bf16 v[68:71], v[176:179], v[220:223], v[68:71]
	v_mfma_f32_16x16x32_bf16 v[64:67], v[188:191], v[220:223], v[64:67]
	s_setprio 0
	s_barrier
	s_add_i32 s71, s47, s30
	v_lshl_add_u64 v[224:225], s[22:23], 0, v[130:131]
	s_mov_b32 m0, s71
	ds_read_b128 v[192:195], v169 offset:16384
	ds_read_b128 v[196:199], v169 offset:17408
	ds_read_b128 v[200:203], v169 offset:18432
	ds_read_b128 v[204:207], v169 offset:19456
	ds_read_b128 v[208:211], v169 offset:20480
	ds_read_b128 v[212:215], v169 offset:21504
	ds_read_b128 v[216:219], v169 offset:22528
	ds_read_b128 v[220:223], v169 offset:23552
	global_load_lds_dwordx4 v[224:225], off
	s_add_i32 m0, s71, 0x2000
	s_add_u32 s72, s22, 0x40000
	v_lshl_add_u64 v[226:227], s[22:23], 0, v[134:135]
	s_addc_u32 s73, s23, 0
	s_add_i32 s71, s48, s30
	global_load_lds_dwordx4 v[226:227], off
	v_lshl_add_u64 v[228:229], s[72:73], 0, v[130:131]
	s_mov_b32 m0, s71
	v_lshl_add_u64 v[230:231], s[24:25], 0, v[132:133]
	global_load_lds_dwordx4 v[228:229], off
	v_lshl_add_u64 v[228:229], s[72:73], 0, v[134:135]
	s_add_i32 m0, s71, 0x2000
	s_nop 0
	global_load_lds_dwordx4 v[228:229], off
	v_lshl_add_u64 v[228:229], s[24:25], 0, v[128:129]
	s_mov_b32 m0, s19
	s_nop 0
	global_load_lds_dwordx4 v[228:229], off
	s_mov_b32 m0, s31
	s_nop 0
	global_load_lds_dwordx4 v[230:231], off
	s_waitcnt vmcnt(8)
	s_waitcnt lgkmcnt(0)
	s_barrier
; #define PG8_STAGE(bufoff, gbase, voff) do { _Pragma("unroll") for (int _i = 0; _i < 2; ++_i) \
;         __builtin_amdgcn_global_load_lds((const unsigned*)((const char*)(gbase) + (voff)[_i]), (PG8_LAS unsigned*)(lds + (bufoff) + ldsw + _i * 8192), 16, 0, 0); } while (0)
; #define PG8_LDA(dst, b, h) do { _Pragma("unroll") for (int m = 0; m < 4; ++m) _Pragma("unroll") for (int k = 0; k < 2; ++k) dst[m][k] = *(const PG8_LAS bf16x8*)(lds + PG8_SA(b, h) + aoff + m * 2048 + k * 1024); } while (0)
; #define PG8_LDB(dst, b, h) do { _Pragma("unroll") for (int n = 0; n < 2; ++n) _Pragma("unroll") for (int k = 0; k < 2; ++k) dst[n][k] = *(const PG8_LAS bf16x8*)(lds + PG8_SB(b, h) + boff + n * 2048 + k * 1024); } while (0)
; #define PG8_MMA(ai, bj, At, Bt) do { __builtin_amdgcn_s_setprio(1); _Pragma("unroll") for (int m = 0; m < 4; ++m) _Pragma("unroll") for (int n = 0; n < 2; ++n) _Pragma("unroll") for (int k = 0; k < 2; ++k) \
;         acc[ai][bj][m][n] = __builtin_amdgcn_mfma_f32_16x16x32_bf16(Bt[n][k], At[m][k], acc[ai][bj][m][n], 0, 0, 0); __builtin_amdgcn_s_setprio(0); } while (0)
; #define PG8_WAIT_V(n) asm volatile("s_waitcnt vmcnt(" #n ")" ::: "memory")
; #define PG8_WAIT_L(n) asm volatile("s_waitcnt lgkmcnt(" #n ")" ::: "memory")
; #define PG8_BAR __builtin_amdgcn_s_barrier()
; #define PG8_SCHED __builtin_amdgcn_sched_barrier(0)
; template <class Epi, class Sched, bool ALIGN_EPI = false, bool SP2 = false>
; __device__ __forceinline__ void gemm_phase(PG8_LAS unsigned char* lds, const Gemm g, const Sched& S, const Epi& E) {
;     ...
;             PG8_WAIT_V(8); PG8_WAIT_L(0); PG8_BAR; PG8_MMA(1, 0, At, B0); PG8_MMA(1, 1, At, B1); PG8_BAR; PG8_SCHED;
;             PG8_LDB(B0, 1, 0); PG8_LDB(B1, 1, 1); PG8_SCHED; PG8_LDA(At, 1, 0); PG8_STAGE(PG8_SA(0, 1), a2 + hstep, voffA);
;             PG8_WAIT_V(8); PG8_WAIT_L(0); PG8_BAR; PG8_MMA(0, 0, At, B0); PG8_MMA(0, 1, At, B1); PG8_BAR; PG8_SCHED;
	s_setprio 1
	s_waitcnt lgkmcnt(0)
	v_mfma_f32_16x16x32_bf16 v[60:63], v[146:149], v[192:195], v[60:63]
	v_mfma_f32_16x16x32_bf16 v[56:59], v[154:157], v[192:195], v[56:59]
	v_mfma_f32_16x16x32_bf16 v[44:47], v[146:149], v[200:203], v[44:47]
	v_mfma_f32_16x16x32_bf16 v[40:43], v[154:157], v[200:203], v[40:43]
	v_mfma_f32_16x16x32_bf16 v[28:31], v[146:149], v[208:211], v[28:31]
	v_mfma_f32_16x16x32_bf16 v[24:27], v[154:157], v[208:211], v[24:27]
	v_mfma_f32_16x16x32_bf16 v[12:15], v[146:149], v[216:219], v[12:15]
	v_mfma_f32_16x16x32_bf16 v[8:11], v[154:157], v[216:219], v[8:11]
	v_mfma_f32_16x16x32_bf16 v[60:63], v[150:153], v[196:199], v[60:63]
	v_mfma_f32_16x16x32_bf16 v[56:59], v[158:161], v[196:199], v[56:59]
	v_mfma_f32_16x16x32_bf16 v[44:47], v[150:153], v[204:207], v[44:47]
	v_mfma_f32_16x16x32_bf16 v[40:43], v[158:161], v[204:207], v[40:43]
	v_mfma_f32_16x16x32_bf16 v[28:31], v[150:153], v[212:215], v[28:31]
	v_mfma_f32_16x16x32_bf16 v[24:27], v[158:161], v[212:215], v[24:27]
	v_mfma_f32_16x16x32_bf16 v[12:15], v[150:153], v[220:223], v[12:15]
	v_mfma_f32_16x16x32_bf16 v[8:11], v[158:161], v[220:223], v[8:11]
	s_setprio 0
	s_setprio 1
	v_mfma_f32_16x16x32_bf16 v[52:55], v[172:175], v[192:195], v[52:55]
	v_mfma_f32_16x16x32_bf16 v[48:51], v[180:183], v[192:195], v[48:51]
	v_mfma_f32_16x16x32_bf16 v[36:39], v[172:175], v[200:203], v[36:39]
	v_mfma_f32_16x16x32_bf16 v[32:35], v[180:183], v[200:203], v[32:35]
	v_mfma_f32_16x16x32_bf16 v[20:23], v[172:175], v[208:211], v[20:23]
	v_mfma_f32_16x16x32_bf16 v[16:19], v[180:183], v[208:211], v[16:19]
	v_mfma_f32_16x16x32_bf16 v[4:7], v[172:175], v[216:219], v[4:7]
	v_mfma_f32_16x16x32_bf16 v[0:3], v[180:183], v[216:219], v[0:3]
	v_mfma_f32_16x16x32_bf16 v[52:55], v[176:179], v[196:199], v[52:55]
	v_mfma_f32_16x16x32_bf16 v[48:51], v[188:191], v[196:199], v[48:51]
	v_mfma_f32_16x16x32_bf16 v[36:39], v[176:179], v[204:207], v[36:39]
	v_mfma_f32_16x16x32_bf16 v[32:35], v[188:191], v[204:207], v[32:35]
	v_mfma_f32_16x16x32_bf16 v[20:23], v[176:179], v[212:215], v[20:23]
	v_mfma_f32_16x16x32_bf16 v[16:19], v[188:191], v[212:215], v[16:19]
	v_mfma_f32_16x16x32_bf16 v[4:7], v[176:179], v[220:223], v[4:7]
	v_mfma_f32_16x16x32_bf16 v[0:3], v[188:191], v[220:223], v[0:3]
	s_setprio 0
	s_barrier
	s_add_i32 s71, 0, 0x18000
	s_add_i32 s72, 0, 0x1c000
	v_add_u32_e32 v158, s71, v164
	v_add_u32_e32 v171, s72, v164
	ds_read_b128 v[146:149], v158
	ds_read_b128 v[150:153], v158 offset:1024
	ds_read_b128 v[154:157], v158 offset:2048
	ds_read_b128 v[158:161], v158 offset:3072
	ds_read_b128 v[172:175], v171
	ds_read_b128 v[176:179], v171 offset:1024
	ds_read_b128 v[180:183], v171 offset:2048
	ds_read_b128 v[188:191], v171 offset:3072
	s_add_u32 s24, s24, 0x40000
	s_addc_u32 s25, s25, 0
	s_mov_b32 m0, s36
	v_lshl_add_u64 v[234:235], s[24:25], 0, v[128:129]
	ds_read_b128 v[192:195], v169 offset:32768
	ds_read_b128 v[196:199], v169 offset:33792
	ds_read_b128 v[200:203], v169 offset:34816
	ds_read_b128 v[204:207], v169 offset:35840
	ds_read_b128 v[208:211], v169 offset:36864
	ds_read_b128 v[212:215], v169 offset:37888
	ds_read_b128 v[216:219], v169 offset:38912
	ds_read_b128 v[220:223], v169 offset:39936
	global_load_lds_dwordx4 v[234:235], off
	v_lshl_add_u64 v[234:235], s[24:25], 0, v[132:133]
	s_mov_b32 m0, s37
	s_nop 0
	global_load_lds_dwordx4 v[234:235], off
	s_waitcnt vmcnt(8)
	s_waitcnt lgkmcnt(0)
	s_barrier
	s_setprio 1
	s_waitcnt lgkmcnt(0)
	v_mfma_f32_16x16x32_bf16 v[124:127], v[146:149], v[192:195], v[124:127]
	v_mfma_f32_16x16x32_bf16 v[120:123], v[154:157], v[192:195], v[120:123]
	v_mfma_f32_16x16x32_bf16 v[116:119], v[146:149], v[200:203], v[116:119]
	v_mfma_f32_16x16x32_bf16 v[112:115], v[154:157], v[200:203], v[112:115]
	v_mfma_f32_16x16x32_bf16 v[92:95], v[146:149], v[208:211], v[92:95]
	v_mfma_f32_16x16x32_bf16 v[88:91], v[154:157], v[208:211], v[88:91]
	v_mfma_f32_16x16x32_bf16 v[76:79], v[146:149], v[216:219], v[76:79]
	v_mfma_f32_16x16x32_bf16 v[72:75], v[154:157], v[216:219], v[72:75]
	v_mfma_f32_16x16x32_bf16 v[124:127], v[150:153], v[196:199], v[124:127]
	v_mfma_f32_16x16x32_bf16 v[120:123], v[158:161], v[196:199], v[120:123]
	v_mfma_f32_16x16x32_bf16 v[116:119], v[150:153], v[204:207], v[116:119]
	v_mfma_f32_16x16x32_bf16 v[112:115], v[158:161], v[204:207], v[112:115]
	v_mfma_f32_16x16x32_bf16 v[92:95], v[150:153], v[212:215], v[92:95]
	v_mfma_f32_16x16x32_bf16 v[88:91], v[158:161], v[212:215], v[88:91]
	v_mfma_f32_16x16x32_bf16 v[76:79], v[150:153], v[220:223], v[76:79]
	v_mfma_f32_16x16x32_bf16 v[72:75], v[158:161], v[220:223], v[72:75]
	s_setprio 0
	s_setprio 1
	v_mfma_f32_16x16x32_bf16 v[108:111], v[172:175], v[192:195], v[108:111]
	v_mfma_f32_16x16x32_bf16 v[104:107], v[180:183], v[192:195], v[104:107]
	v_mfma_f32_16x16x32_bf16 v[100:103], v[172:175], v[200:203], v[100:103]
	v_mfma_f32_16x16x32_bf16 v[96:99], v[180:183], v[200:203], v[96:99]
	v_mfma_f32_16x16x32_bf16 v[84:87], v[172:175], v[208:211], v[84:87]
	v_mfma_f32_16x16x32_bf16 v[80:83], v[180:183], v[208:211], v[80:83]
	v_mfma_f32_16x16x32_bf16 v[68:71], v[172:175], v[216:219], v[68:71]
	v_mfma_f32_16x16x32_bf16 v[64:67], v[180:183], v[216:219], v[64:67]
	v_mfma_f32_16x16x32_bf16 v[108:111], v[176:179], v[196:199], v[108:111]
	v_mfma_f32_16x16x32_bf16 v[104:107], v[188:191], v[196:199], v[104:107]
	v_mfma_f32_16x16x32_bf16 v[100:103], v[176:179], v[204:207], v[100:103]
	v_mfma_f32_16x16x32_bf16 v[96:99], v[188:191], v[204:207], v[96:99]
	v_mfma_f32_16x16x32_bf16 v[84:87], v[176:179], v[212:215], v[84:87]
	v_mfma_f32_16x16x32_bf16 v[80:83], v[188:191], v[212:215], v[80:83]
	v_mfma_f32_16x16x32_bf16 v[68:71], v[176:179], v[220:223], v[68:71]
	v_mfma_f32_16x16x32_bf16 v[64:67], v[188:191], v[220:223], v[64:67]
	s_setprio 0
	s_barrier
; #define PG8_STAGE(bufoff, gbase, voff) do { _Pragma("unroll") for (int _i = 0; _i < 2; ++_i) \
;         __builtin_amdgcn_global_load_lds((const unsigned*)((const char*)(gbase) + (voff)[_i]), (PG8_LAS unsigned*)(lds + (bufoff) + ldsw + _i * 8192), 16, 0, 0); } while (0)
; #define PG8_LDA(dst, b, h) do { _Pragma("unroll") for (int m = 0; m < 4; ++m) _Pragma("unroll") for (int k = 0; k < 2; ++k) dst[m][k] = *(const PG8_LAS bf16x8*)(lds + PG8_SA(b, h) + aoff + m * 2048 + k * 1024); } while (0)
; #define PG8_MMA(ai, bj, At, Bt) do { __builtin_amdgcn_s_setprio(1); _Pragma("unroll") for (int m = 0; m < 4; ++m) _Pragma("unroll") for (int n = 0; n < 2; ++n) _Pragma("unroll") for (int k = 0; k < 2; ++k) \
;         acc[ai][bj][m][n] = __builtin_amdgcn_mfma_f32_16x16x32_bf16(Bt[n][k], At[m][k], acc[ai][bj][m][n], 0, 0, 0); __builtin_amdgcn_s_setprio(0); } while (0)
; #define PG8_WAIT_V(n) asm volatile("s_waitcnt vmcnt(" #n ")" ::: "memory")
; #define PG8_WAIT_L(n) asm volatile("s_waitcnt lgkmcnt(" #n ")" ::: "memory")
; #define PG8_BAR __builtin_amdgcn_s_barrier()
; #define PG8_SCHED __builtin_amdgcn_sched_barrier(0)
;     __device__ __forceinline__ void operator()(const f32x4 (&acc)[2][2][4][2], const Unit& u, int wr, int wc, int fr, int fq) const {
;         const int row0 = u.pm * BM + wr * 64 + fr, col0 = u.pn * BM + wc * 32 + 8 * fq;
;         f32x4 cs[2][2];
; #pragma unroll
;         for (int bj = 0; bj < 2; ++bj)
; #pragma unroll
;             for (int n = 0; n < 2; ++n) { const f32x4 q = *(const f32x4*)(ssq + col0 + bj * HALF + 4 * n);
; template <class Epi, class Sched, bool ALIGN_EPI = false, bool SP2 = false>
; __device__ __forceinline__ void gemm_phase(PG8_LAS unsigned char* lds, const Gemm g, const Sched& S, const Epi& E) {
;     ...
;             PG8_LDA(At, 1, 1); PG8_STAGE(PG8_SB(1, 0), b3, voffB); PG8_STAGE(PG8_SB(1, 1), b3 + hstep, voffB); PG8_STAGE(PG8_SA(1, 0), a3, voffA);
;             PG8_WAIT_V(8); PG8_WAIT_L(0); PG8_BAR; PG8_MMA(1, 0, At, B0); PG8_MMA(1, 1, At, B1); PG8_BAR; PG8_SCHED;
	s_add_i32 s24, s71, s30
	v_lshl_add_u64 v[224:225], v[224:225], 0, s[4:5]
	s_mov_b32 m0, s24
	ds_read_b128 v[192:195], v169 offset:49152
	ds_read_b128 v[196:199], v169 offset:50176
	ds_read_b128 v[200:203], v169 offset:51200
	ds_read_b128 v[204:207], v169 offset:52224
	ds_read_b128 v[208:211], v169 offset:53248
	ds_read_b128 v[212:215], v169 offset:54272
	ds_read_b128 v[216:219], v169 offset:55296
	ds_read_b128 v[220:223], v169 offset:56320
	global_load_lds_dwordx4 v[224:225], off
	s_add_i32 m0, s24, 0x2000
	s_add_u32 s22, s22, 0x40080
	v_lshl_add_u64 v[224:225], v[226:227], 0, s[4:5]
	s_addc_u32 s23, s23, 0
	s_add_i32 s24, s72, s30
	global_load_lds_dwordx4 v[224:225], off
	v_lshl_add_u64 v[224:225], s[22:23], 0, v[130:131]
	s_mov_b32 m0, s24
	s_nop 0
	global_load_lds_dwordx4 v[224:225], off
	v_lshl_add_u64 v[224:225], s[22:23], 0, v[134:135]
	s_add_i32 m0, s24, 0x2000
	s_nop 0
	global_load_lds_dwordx4 v[224:225], off
	v_lshl_add_u64 v[224:225], v[228:229], 0, s[4:5]
	s_mov_b32 m0, s43
	s_nop 0
	global_load_lds_dwordx4 v[224:225], off
	v_lshl_add_u64 v[224:225], v[230:231], 0, s[4:5]
	s_mov_b32 m0, s44
	s_nop 0
	global_load_lds_dwordx4 v[224:225], off
	s_waitcnt vmcnt(8)
	s_waitcnt lgkmcnt(0)
	s_barrier
	s_setprio 1
	s_waitcnt lgkmcnt(0)
	v_mfma_f32_16x16x32_bf16 v[60:63], v[146:149], v[192:195], v[60:63]
	v_mfma_f32_16x16x32_bf16 v[56:59], v[154:157], v[192:195], v[56:59]
	v_mfma_f32_16x16x32_bf16 v[44:47], v[146:149], v[200:203], v[44:47]
	v_mfma_f32_16x16x32_bf16 v[40:43], v[154:157], v[200:203], v[40:43]
	v_mfma_f32_16x16x32_bf16 v[28:31], v[146:149], v[208:211], v[28:31]
	v_mfma_f32_16x16x32_bf16 v[24:27], v[154:157], v[208:211], v[24:27]
	v_mfma_f32_16x16x32_bf16 v[12:15], v[146:149], v[216:219], v[12:15]
	v_mfma_f32_16x16x32_bf16 v[8:11], v[154:157], v[216:219], v[8:11]
	v_mfma_f32_16x16x32_bf16 v[60:63], v[150:153], v[196:199], v[60:63]
	v_mfma_f32_16x16x32_bf16 v[56:59], v[158:161], v[196:199], v[56:59]
	v_mfma_f32_16x16x32_bf16 v[44:47], v[150:153], v[204:207], v[44:47]
	v_mfma_f32_16x16x32_bf16 v[40:43], v[158:161], v[204:207], v[40:43]
	v_mfma_f32_16x16x32_bf16 v[28:31], v[150:153], v[212:215], v[28:31]
	v_mfma_f32_16x16x32_bf16 v[24:27], v[158:161], v[212:215], v[24:27]
	v_mfma_f32_16x16x32_bf16 v[12:15], v[150:153], v[220:223], v[12:15]
	v_mfma_f32_16x16x32_bf16 v[8:11], v[158:161], v[220:223], v[8:11]
	s_setprio 0
	s_setprio 1
	v_mfma_f32_16x16x32_bf16 v[52:55], v[172:175], v[192:195], v[52:55]
	v_mfma_f32_16x16x32_bf16 v[48:51], v[180:183], v[192:195], v[48:51]
	v_mfma_f32_16x16x32_bf16 v[36:39], v[172:175], v[200:203], v[36:39]
	v_mfma_f32_16x16x32_bf16 v[32:35], v[180:183], v[200:203], v[32:35]
	v_mfma_f32_16x16x32_bf16 v[20:23], v[172:175], v[208:211], v[20:23]
	v_mfma_f32_16x16x32_bf16 v[16:19], v[180:183], v[208:211], v[16:19]
	v_mfma_f32_16x16x32_bf16 v[4:7], v[172:175], v[216:219], v[4:7]
	v_mfma_f32_16x16x32_bf16 v[0:3], v[180:183], v[216:219], v[0:3]
	v_mfma_f32_16x16x32_bf16 v[52:55], v[176:179], v[196:199], v[52:55]
	v_mfma_f32_16x16x32_bf16 v[48:51], v[188:191], v[196:199], v[48:51]
	v_mfma_f32_16x16x32_bf16 v[36:39], v[176:179], v[204:207], v[36:39]
	v_mfma_f32_16x16x32_bf16 v[32:35], v[188:191], v[204:207], v[32:35]
	v_mfma_f32_16x16x32_bf16 v[20:23], v[176:179], v[212:215], v[20:23]
	v_mfma_f32_16x16x32_bf16 v[16:19], v[188:191], v[212:215], v[16:19]
	v_mfma_f32_16x16x32_bf16 v[4:7], v[176:179], v[220:223], v[4:7]
	v_mfma_f32_16x16x32_bf16 v[0:3], v[188:191], v[220:223], v[0:3]
	s_setprio 0
	s_barrier
	s_add_i32 s70, s70, 2
	s_add_u32 s20, s20, 0x100
	s_addc_u32 s21, s21, 0
	s_add_u32 s58, s58, 0x100
	s_addc_u32 s69, s69, 0
	s_cmp_gt_u32 s70, 13
	s_cbranch_scc0 .LBB0_576
	s_lshl_b32 s11, s49, 8
	s_or_b32 s11, s11, s42
	v_or_b32_e32 v146, s11, v163
	v_ashrrev_i32_e32 v147, 31, v146
	v_lshl_add_u64 v[158:159], v[146:147], 2, s[8:9]
	global_load_dwordx4 v[146:149], v[158:159], off
	global_load_dwordx4 v[150:153], v[158:159], off offset:16
	global_load_dwordx4 v[154:157], v[158:159], off offset:512
	s_nop 0
	global_load_dwordx4 v[158:161], v[158:159], off offset:528
	s_lshl_b32 s20, s18, 8
	s_add_i32 s20, s20, s39
	s_and_b32 s18, s49, 0x7ffff0
	s_lshr_b32 s13, s20, 6
	s_lshr_b32 s11, s11, 3
	s_add_i32 s13, s13, s18
	s_and_b32 s11, s11, 0x1ec
	v_lshl_or_b32 v171, s13, 9, v165
	s_or_b32 s13, s11, 16
	v_or_b32_e32 v172, s11, v171
	v_or_b32_e32 v173, s13, v171
	v_lshlrev_b32_e32 v175, 6, v172
	v_lshlrev_b32_e32 v173, 6, v173
	v_or_b32_e32 v172, v175, v162
	v_or_b32_e32 v174, v173, v162
	v_or_b32_e32 v176, v175, v166
	v_or_b32_e32 v178, v173, v166
	v_ashrrev_i32_e32 v173, 31, v172
	v_ashrrev_i32_e32 v175, 31, v174
	v_lshl_add_u64 v[172:173], v[172:173], 4, v[136:137]
	v_lshl_add_u64 v[174:175], v[174:175], 4, v[136:137]
	v_ashrrev_i32_e32 v177, 31, v176
	v_lshl_add_u64 v[176:177], v[176:177], 4, v[136:137]
	s_addk_i32 s20, 0x80
	s_lshr_b32 s20, s20, 6
	s_add_i32 s20, s20, s18
	s_and_b64 vcc, exec, s[2:3]
	s_mov_b32 s49, s10
	s_mov_b32 s18, s12
	s_mov_b64 s[22:23], s[16:17]
	s_waitcnt vmcnt(0)
; __device__ __forceinline__ unsigned cvt_pk_bf16(float lo, float hi) { unsigned r; asm volatile("v_cvt_pk_bf16_f32 %0, %1, %2" : "=v"(r) : "v"(lo), "v"(hi)); return r; }
;     __device__ __forceinline__ void operator()(const f32x4 (&acc)[2][2][4][2], const Unit& u, int wr, int wc, int fr, int fq) const {
;     ...
;             for (int n = 0; n < 2; ++n) { const f32x4 q = *(const f32x4*)(ssq + col0 + bj * HALF + 4 * n);
; #pragma unroll
;                 for (int e = 0; e < 4; ++e) cs[bj][n][e] = __builtin_amdgcn_rsqf(q[e] * (1.0f / 1024.0f) + 1e-6f); }
; #pragma unroll
;         for (int ai = 0; ai < 2; ++ai)
; #pragma unroll
;             for (int m = 0; m < 4; ++m) { const int row = row0 + ai * HALF + m * 16, h = row >> 6, d = row & 63, dt = d >> 5, r = d & 31;
; #pragma unroll
;                 for (int bj = 0; bj < 2; ++bj) { const int col = col0 + bj * HALF, b = col >> 12, tl = col & 4095, kt = tl >> 5, k0 = tl & 31, s = k0 >> 4, half = (k0 >> 3) & 1, bh = b * 16 + h;
;                     const f32x4 v0 = acc[ai][bj][m][0] * cs[bj][0], v1 = acc[ai][bj][m][1] * cs[bj][1];
;                     bf16_t* p = VF + (((size_t)((((bh * 128 + kt) * 2 + dt) * 2 + s) * 64 + r)) << 3) + 4 * half;
;                     *(unsigned long long*)p = (unsigned long long)cvt_pk_bf16(v0[0], v0[1]) | ((unsigned long long)cvt_pk_bf16(v0[2], v0[3]) << 32);
;                     *(unsigned long long*)(p + 256) = (unsigned long long)cvt_pk_bf16(v1[0], v1[1]) | ((unsigned long long)cvt_pk_bf16(v1[2], v1[3]) << 32); }
	v_fmamk_f32 v146, v146, 0x3a800000, v170
	v_fmamk_f32 v147, v147, 0x3a800000, v170
	v_fmamk_f32 v148, v148, 0x3a800000, v170
	v_fmamk_f32 v149, v149, 0x3a800000, v170
	v_fmamk_f32 v150, v150, 0x3a800000, v170
	v_fmamk_f32 v151, v151, 0x3a800000, v170
	v_fmamk_f32 v179, v154, 0x3a800000, v170
	v_fmamk_f32 v180, v155, 0x3a800000, v170
	v_fmamk_f32 v183, v158, 0x3a800000, v170
	v_fmamk_f32 v185, v159, 0x3a800000, v170
	v_fmamk_f32 v152, v152, 0x3a800000, v170
	v_fmamk_f32 v153, v153, 0x3a800000, v170
	v_fmamk_f32 v181, v156, 0x3a800000, v170
	v_fmamk_f32 v182, v157, 0x3a800000, v170
	v_fmamk_f32 v187, v160, 0x3a800000, v170
	v_fmamk_f32 v188, v161, 0x3a800000, v170
	v_rsq_f32_e32 v156, v146
	v_rsq_f32_e32 v157, v147
	v_rsq_f32_e32 v160, v148
	v_rsq_f32_e32 v161, v149
	v_rsq_f32_e32 v154, v150
	v_rsq_f32_e32 v155, v151
	v_rsq_f32_e32 v148, v179
	v_rsq_f32_e32 v149, v180
	v_rsq_f32_e32 v146, v183
	v_rsq_f32_e32 v147, v185
	v_rsq_f32_e32 v158, v152
	v_rsq_f32_e32 v159, v153
	v_rsq_f32_e32 v152, v181
	v_rsq_f32_e32 v153, v182
	v_rsq_f32_e32 v150, v187
	v_rsq_f32_e32 v151, v188
	v_pk_mul_f32 v[124:125], v[124:125], v[156:157]
	v_pk_mul_f32 v[120:121], v[120:121], v[154:155]
	v_pk_mul_f32 v[108:109], v[108:109], v[148:149]
	v_pk_mul_f32 v[104:105], v[104:105], v[146:147]
	v_pk_mul_f32 v[126:127], v[126:127], v[160:161]
	v_pk_mul_f32 v[122:123], v[122:123], v[158:159]
	v_pk_mul_f32 v[110:111], v[110:111], v[152:153]
	v_pk_mul_f32 v[106:107], v[106:107], v[150:151]
	v_cvt_pk_bf16_f32 v188, v124, v125
	v_cvt_pk_bf16_f32 v189, v126, v127
	v_cvt_pk_bf16_f32 v190, v120, v121
	v_cvt_pk_bf16_f32 v191, v122, v123
	s_nop 1
	v_permlane16_swap_b32_e32 v188, v190
	v_permlane16_swap_b32_e32 v189, v191
	global_store_dwordx4 v[172:173], v[188:191], off
	v_cvt_pk_bf16_f32 v192, v108, v109
	v_cvt_pk_bf16_f32 v193, v110, v111
	v_cvt_pk_bf16_f32 v194, v104, v105
	v_cvt_pk_bf16_f32 v195, v106, v107
	s_nop 1
	v_permlane16_swap_b32_e32 v192, v194
	v_permlane16_swap_b32_e32 v193, v195
	global_store_dwordx4 v[174:175], v[192:195], off
	v_pk_mul_f32 v[118:119], v[118:119], v[160:161]
	v_pk_mul_f32 v[116:117], v[116:117], v[156:157]
	v_pk_mul_f32 v[114:115], v[114:115], v[158:159]
	v_cvt_pk_bf16_f32 v196, v116, v117
	v_cvt_pk_bf16_f32 v197, v118, v119
	v_pk_mul_f32 v[112:113], v[112:113], v[154:155]
	v_cvt_pk_bf16_f32 v198, v112, v113
	v_cvt_pk_bf16_f32 v199, v114, v115
	v_ashrrev_i32_e32 v179, 31, v178
	v_pk_mul_f32 v[100:101], v[100:101], v[148:149]
	v_pk_mul_f32 v[98:99], v[98:99], v[150:151]
	v_pk_mul_f32 v[96:97], v[96:97], v[146:147]
	s_nop 1
	v_permlane16_swap_b32_e32 v196, v198
	v_permlane16_swap_b32_e32 v197, v199
	global_store_dwordx4 v[176:177], v[196:199], off
	v_lshl_add_u64 v[104:105], v[178:179], 4, v[136:137]
	v_pk_mul_f32 v[102:103], v[102:103], v[152:153]
	v_cvt_pk_bf16_f32 v200, v100, v101
	v_pk_mul_f32 v[92:93], v[92:93], v[156:157]
	v_cvt_pk_bf16_f32 v201, v102, v103
	v_cvt_pk_bf16_f32 v202, v96, v97
	v_cvt_pk_bf16_f32 v203, v98, v99
	v_or_b32_e32 v98, 2, v171
	s_nop 1
	v_permlane16_swap_b32_e32 v200, v202
	v_permlane16_swap_b32_e32 v201, v203
	global_store_dwordx4 v[104:105], v[200:203], off
	v_or_b32_e32 v96, s11, v98
	v_lshlrev_b32_e32 v99, 6, v96
	v_or_b32_e32 v96, v99, v162
	v_ashrrev_i32_e32 v97, 31, v96
	v_pk_mul_f32 v[88:89], v[88:89], v[154:155]
	v_lshl_add_u64 v[96:97], v[96:97], 4, v[136:137]
	v_pk_mul_f32 v[94:95], v[94:95], v[160:161]
	v_cvt_pk_bf16_f32 v188, v92, v93
	v_pk_mul_f32 v[90:91], v[90:91], v[158:159]
	v_cvt_pk_bf16_f32 v189, v94, v95
	v_cvt_pk_bf16_f32 v190, v88, v89
	v_cvt_pk_bf16_f32 v191, v90, v91
	s_nop 1
	v_permlane16_swap_b32_e32 v188, v190
	v_permlane16_swap_b32_e32 v189, v191
	global_store_dwordx4 v[96:97], v[188:191], off
	v_or_b32_e32 v88, s13, v98
	v_lshlrev_b32_e32 v90, 6, v88
	v_or_b32_e32 v88, v90, v162
	v_ashrrev_i32_e32 v89, 31, v88
	v_pk_mul_f32 v[84:85], v[84:85], v[148:149]
	v_pk_mul_f32 v[80:81], v[80:81], v[146:147]
	v_lshl_add_u64 v[88:89], v[88:89], 4, v[136:137]
	v_pk_mul_f32 v[86:87], v[86:87], v[152:153]
	v_cvt_pk_bf16_f32 v192, v84, v85
	v_pk_mul_f32 v[82:83], v[82:83], v[150:151]
	v_cvt_pk_bf16_f32 v193, v86, v87
	v_cvt_pk_bf16_f32 v194, v80, v81
	v_cvt_pk_bf16_f32 v195, v82, v83
	s_nop 1
	v_permlane16_swap_b32_e32 v192, v194
	v_permlane16_swap_b32_e32 v193, v195
	global_store_dwordx4 v[88:89], v[192:195], off
	v_or_b32_e32 v80, v99, v166
	v_ashrrev_i32_e32 v81, 31, v80
	v_pk_mul_f32 v[76:77], v[76:77], v[156:157]
	v_pk_mul_f32 v[72:73], v[72:73], v[154:155]
	v_lshl_add_u64 v[80:81], v[80:81], 4, v[136:137]
	v_pk_mul_f32 v[78:79], v[78:79], v[160:161]
	v_cvt_pk_bf16_f32 v196, v76, v77
	v_pk_mul_f32 v[74:75], v[74:75], v[158:159]
	v_cvt_pk_bf16_f32 v197, v78, v79
	v_cvt_pk_bf16_f32 v198, v72, v73
	v_cvt_pk_bf16_f32 v199, v74, v75
	s_nop 1
	v_permlane16_swap_b32_e32 v196, v198
	v_permlane16_swap_b32_e32 v197, v199
	global_store_dwordx4 v[80:81], v[196:199], off
	v_or_b32_e32 v72, v90, v166
	v_ashrrev_i32_e32 v73, 31, v72
	v_pk_mul_f32 v[68:69], v[68:69], v[148:149]
	v_pk_mul_f32 v[66:67], v[66:67], v[150:151]
	v_pk_mul_f32 v[64:65], v[64:65], v[146:147]
	v_lshl_add_u64 v[72:73], v[72:73], 4, v[136:137]
	v_pk_mul_f32 v[70:71], v[70:71], v[152:153]
; __device__ __forceinline__ unsigned cvt_pk_bf16(float lo, float hi) { unsigned r; asm volatile("v_cvt_pk_bf16_f32 %0, %1, %2" : "=v"(r) : "v"(lo), "v"(hi)); return r; }
;     __device__ __forceinline__ void operator()(const f32x4 (&acc)[2][2][4][2], const Unit& u, int wr, int wc, int fr, int fq) const {
;     ...
;         for (int ai = 0; ai < 2; ++ai)
; #pragma unroll
;             for (int m = 0; m < 4; ++m) { const int row = row0 + ai * HALF + m * 16, h = row >> 6, d = row & 63, dt = d >> 5, r = d & 31;
; #pragma unroll
;                 for (int bj = 0; bj < 2; ++bj) { const int col = col0 + bj * HALF, b = col >> 12, tl = col & 4095, kt = tl >> 5, k0 = tl & 31, s = k0 >> 4, half = (k0 >> 3) & 1, bh = b * 16 + h;
;                     const f32x4 v0 = acc[ai][bj][m][0] * cs[bj][0], v1 = acc[ai][bj][m][1] * cs[bj][1];
;                     bf16_t* p = VF + (((size_t)((((bh * 128 + kt) * 2 + dt) * 2 + s) * 64 + r)) << 3) + 4 * half;
;                     *(unsigned long long*)p = (unsigned long long)cvt_pk_bf16(v0[0], v0[1]) | ((unsigned long long)cvt_pk_bf16(v0[2], v0[3]) << 32);
;                     *(unsigned long long*)(p + 256) = (unsigned long long)cvt_pk_bf16(v1[0], v1[1]) | ((unsigned long long)cvt_pk_bf16(v1[2], v1[3]) << 32); }
;                 asm volatile("" ::: "memory"); }
	v_cvt_pk_bf16_f32 v200, v68, v69
	v_pk_mul_f32 v[60:61], v[60:61], v[156:157]
	v_cvt_pk_bf16_f32 v201, v70, v71
	v_cvt_pk_bf16_f32 v202, v64, v65
	v_cvt_pk_bf16_f32 v203, v66, v67
	v_lshl_or_b32 v66, s20, 9, v165
	s_nop 1
	v_permlane16_swap_b32_e32 v200, v202
	v_permlane16_swap_b32_e32 v201, v203
	global_store_dwordx4 v[72:73], v[200:203], off
	v_or_b32_e32 v64, s11, v66
	v_lshlrev_b32_e32 v67, 6, v64
	v_or_b32_e32 v64, v67, v162
	v_ashrrev_i32_e32 v65, 31, v64
	v_pk_mul_f32 v[56:57], v[56:57], v[154:155]
	v_lshl_add_u64 v[64:65], v[64:65], 4, v[136:137]
	v_pk_mul_f32 v[62:63], v[62:63], v[160:161]
	v_cvt_pk_bf16_f32 v188, v60, v61
	v_pk_mul_f32 v[58:59], v[58:59], v[158:159]
	v_cvt_pk_bf16_f32 v189, v62, v63
	v_cvt_pk_bf16_f32 v190, v56, v57
	v_cvt_pk_bf16_f32 v191, v58, v59
	s_nop 1
	v_permlane16_swap_b32_e32 v188, v190
	v_permlane16_swap_b32_e32 v189, v191
	global_store_dwordx4 v[64:65], v[188:191], off
	v_or_b32_e32 v56, s13, v66
	v_lshlrev_b32_e32 v58, 6, v56
	v_or_b32_e32 v56, v58, v162
	v_ashrrev_i32_e32 v57, 31, v56
	v_pk_mul_f32 v[52:53], v[52:53], v[148:149]
	v_pk_mul_f32 v[48:49], v[48:49], v[146:147]
	v_lshl_add_u64 v[56:57], v[56:57], 4, v[136:137]
	v_pk_mul_f32 v[54:55], v[54:55], v[152:153]
	v_cvt_pk_bf16_f32 v192, v52, v53
	v_pk_mul_f32 v[50:51], v[50:51], v[150:151]
	v_cvt_pk_bf16_f32 v193, v54, v55
	v_cvt_pk_bf16_f32 v194, v48, v49
	v_cvt_pk_bf16_f32 v195, v50, v51
	s_nop 1
	v_permlane16_swap_b32_e32 v192, v194
	v_permlane16_swap_b32_e32 v193, v195
	global_store_dwordx4 v[56:57], v[192:195], off
	v_or_b32_e32 v48, v67, v166
	v_ashrrev_i32_e32 v49, 31, v48
	v_pk_mul_f32 v[44:45], v[44:45], v[156:157]
	v_pk_mul_f32 v[40:41], v[40:41], v[154:155]
	v_lshl_add_u64 v[48:49], v[48:49], 4, v[136:137]
	v_pk_mul_f32 v[46:47], v[46:47], v[160:161]
	v_cvt_pk_bf16_f32 v196, v44, v45
	v_pk_mul_f32 v[42:43], v[42:43], v[158:159]
	v_cvt_pk_bf16_f32 v197, v46, v47
	v_cvt_pk_bf16_f32 v198, v40, v41
	v_cvt_pk_bf16_f32 v199, v42, v43
	s_nop 1
	v_permlane16_swap_b32_e32 v196, v198
	v_permlane16_swap_b32_e32 v197, v199
	global_store_dwordx4 v[48:49], v[196:199], off
	v_or_b32_e32 v40, v58, v166
	v_ashrrev_i32_e32 v41, 31, v40
	v_pk_mul_f32 v[36:37], v[36:37], v[148:149]
	v_pk_mul_f32 v[34:35], v[34:35], v[150:151]
	v_pk_mul_f32 v[32:33], v[32:33], v[146:147]
	v_lshl_add_u64 v[40:41], v[40:41], 4, v[136:137]
	v_pk_mul_f32 v[38:39], v[38:39], v[152:153]
	v_cvt_pk_bf16_f32 v200, v36, v37
	v_pk_mul_f32 v[28:29], v[28:29], v[156:157]
	v_cvt_pk_bf16_f32 v201, v38, v39
	v_cvt_pk_bf16_f32 v202, v32, v33
	v_cvt_pk_bf16_f32 v203, v34, v35
	v_or_b32_e32 v34, 2, v66
	s_nop 1
	v_permlane16_swap_b32_e32 v200, v202
	v_permlane16_swap_b32_e32 v201, v203
	global_store_dwordx4 v[40:41], v[200:203], off
	v_or_b32_e32 v32, s11, v34
	v_lshlrev_b32_e32 v35, 6, v32
	v_or_b32_e32 v32, v35, v162
	v_ashrrev_i32_e32 v33, 31, v32
	v_pk_mul_f32 v[24:25], v[24:25], v[154:155]
	v_lshl_add_u64 v[32:33], v[32:33], 4, v[136:137]
	v_pk_mul_f32 v[30:31], v[30:31], v[160:161]
	v_cvt_pk_bf16_f32 v188, v28, v29
	v_pk_mul_f32 v[26:27], v[26:27], v[158:159]
	v_cvt_pk_bf16_f32 v189, v30, v31
	v_cvt_pk_bf16_f32 v190, v24, v25
	v_cvt_pk_bf16_f32 v191, v26, v27
	s_nop 1
	v_permlane16_swap_b32_e32 v188, v190
	v_permlane16_swap_b32_e32 v189, v191
	global_store_dwordx4 v[32:33], v[188:191], off
	v_or_b32_e32 v24, s13, v34
	v_lshlrev_b32_e32 v26, 6, v24
	v_or_b32_e32 v24, v26, v162
	v_ashrrev_i32_e32 v25, 31, v24
	v_pk_mul_f32 v[20:21], v[20:21], v[148:149]
	v_pk_mul_f32 v[16:17], v[16:17], v[146:147]
	v_lshl_add_u64 v[24:25], v[24:25], 4, v[136:137]
	v_pk_mul_f32 v[22:23], v[22:23], v[152:153]
	v_cvt_pk_bf16_f32 v192, v20, v21
	v_pk_mul_f32 v[18:19], v[18:19], v[150:151]
	v_cvt_pk_bf16_f32 v193, v22, v23
	v_cvt_pk_bf16_f32 v194, v16, v17
	v_cvt_pk_bf16_f32 v195, v18, v19
	s_nop 1
	v_permlane16_swap_b32_e32 v192, v194
	v_permlane16_swap_b32_e32 v193, v195
	global_store_dwordx4 v[24:25], v[192:195], off
	v_or_b32_e32 v16, v35, v166
	v_ashrrev_i32_e32 v17, 31, v16
	v_pk_mul_f32 v[12:13], v[12:13], v[156:157]
	v_pk_mul_f32 v[8:9], v[8:9], v[154:155]
	v_lshl_add_u64 v[16:17], v[16:17], 4, v[136:137]
	v_pk_mul_f32 v[14:15], v[14:15], v[160:161]
	v_cvt_pk_bf16_f32 v196, v12, v13
	v_pk_mul_f32 v[10:11], v[10:11], v[158:159]
	v_cvt_pk_bf16_f32 v197, v14, v15
	v_cvt_pk_bf16_f32 v198, v8, v9
	v_cvt_pk_bf16_f32 v199, v10, v11
	s_nop 1
	v_permlane16_swap_b32_e32 v196, v198
	v_permlane16_swap_b32_e32 v197, v199
	global_store_dwordx4 v[16:17], v[196:199], off
	v_or_b32_e32 v8, v26, v166
	v_ashrrev_i32_e32 v9, 31, v8
	v_pk_mul_f32 v[4:5], v[4:5], v[148:149]
	v_pk_mul_f32 v[0:1], v[0:1], v[146:147]
	v_lshl_add_u64 v[8:9], v[8:9], 4, v[136:137]
	v_pk_mul_f32 v[6:7], v[6:7], v[152:153]
	v_pk_mul_f32 v[2:3], v[2:3], v[150:151]
	v_cvt_pk_bf16_f32 v200, v4, v5
	v_cvt_pk_bf16_f32 v201, v6, v7
	v_cvt_pk_bf16_f32 v202, v0, v1
	v_cvt_pk_bf16_f32 v203, v2, v3
	s_nop 1
	v_permlane16_swap_b32_e32 v200, v202
	v_permlane16_swap_b32_e32 v201, v203
	global_store_dwordx4 v[8:9], v[200:203], off
	s_mov_b64 s[20:21], s[14:15]
	s_cbranch_vccz .LBB0_569
	s_waitcnt vmcnt(0)
	s_cmpk_gt_u32 s26, 0xff
	s_cbranch_scc1 .LBB0_580
	s_barrier
